# v23: v17 + grid barrier arrival atomic issued before the LDS state read
# speedup vs baseline: 1.0029x; 1.0029x over previous
.LBB0_276:
	s_cmp_lt_i32 s59, 2
	s_barrier
	s_cbranch_scc1 .LBB0_330
	s_waitcnt vmcnt(0)
	s_barrier
	s_and_saveexec_b64 s[2:3], s[0:1]
	s_cbranch_execz .LBB0_329
	s_waitcnt vmcnt(0) lgkmcnt(0)
	v_mov_b32_e32 v241, 0
	v_lshlrev_b32_e64 v245, 8, s31
	v_mov_b32_e32 v247, 1
	v_add_u32_e32 v246, 0x1400, v245
	global_atomic_add v248, v246, v247, s[60:61] sc0
.Lxb0_top:
	ds_read_b96 v[242:244], v241
	s_waitcnt lgkmcnt(0)
	v_cmp_ne_u32_e32 vcc, 0, v242
	s_cbranch_vccz .Lxb0_census
.Lxb0_go:
	v_add_u32_e32 v249, 1, v244
	ds_write_b32 v241, v249 offset:8
	v_mul_lo_u32 v250, v249, v242
	v_mul_lo_u32 v251, v249, v243
	v_add_u32_e32 v253, 0x2400, v245
	v_mov_b32_e32 v252, 0
	s_waitcnt vmcnt(0)
	buffer_inv sc1
	v_add_u32_e32 v248, 1, v248
	v_cmp_eq_u32_e32 vcc, v248, v250
	s_cbranch_vccz .Lxb0_wait
	buffer_wbl2 sc1
	s_waitcnt vmcnt(0)
	v_mov_b32_e32 v246, 0x3400
	global_atomic_add v248, v246, v247, s[60:61] sc0
	s_waitcnt vmcnt(0)
	v_add_u32_e32 v248, 1, v248
	v_cmp_ge_u32_e32 vcc, v248, v251
	s_cbranch_vccz .Lxb0_wait
	v_mov_b32_e32 v246, 0x2400
	global_atomic_add v246, v247, s[60:61]
	global_atomic_add v246, v247, s[60:61] offset:256
	global_atomic_add v246, v247, s[60:61] offset:512
	global_atomic_add v246, v247, s[60:61] offset:768
	global_atomic_add v246, v247, s[60:61] offset:1024
	global_atomic_add v246, v247, s[60:61] offset:1280
	global_atomic_add v246, v247, s[60:61] offset:1536
	global_atomic_add v246, v247, s[60:61] offset:1792
	global_atomic_add v246, v247, s[60:61] offset:2048
	global_atomic_add v246, v247, s[60:61] offset:2304
	global_atomic_add v246, v247, s[60:61] offset:2560
	global_atomic_add v246, v247, s[60:61] offset:2816
	global_atomic_add v246, v247, s[60:61] offset:3072
	global_atomic_add v246, v247, s[60:61] offset:3328
	global_atomic_add v246, v247, s[60:61] offset:3584
	global_atomic_add v246, v247, s[60:61] offset:3840
	s_branch .Lxb0_done

.Lxb0_census:
	s_load_dwordx2 s[98:99], s[62:63], 0x4
	v_mov_b32_e32 v252, 0
	v_mov_b32_e32 v253, 0x1000
	s_waitcnt lgkmcnt(0)
	s_mul_i32 s98, s98, s56
	s_mul_i32 s98, s98, s99
	s_waitcnt vmcnt(0)
	v_readfirstlane_b32 s99, v248

.Lxb0_top2:
	ds_read_b96 v[242:244], v241
	v_lshlrev_b32_e64 v245, 8, s31
	v_mov_b32_e32 v247, 1
	v_mov_b32_e32 v248, s99
	s_waitcnt lgkmcnt(0)
	s_branch .Lxb0_go

.LBB0_338:
	s_cmp_lt_i32 s59, 3
	s_barrier
	s_cbranch_scc1 .LBB0_392
	s_waitcnt vmcnt(0)
	s_barrier
	s_and_saveexec_b64 s[2:3], s[0:1]
	s_cbranch_execz .LBB0_391
	s_waitcnt vmcnt(0) lgkmcnt(0)
	v_mov_b32_e32 v241, 0
	v_lshlrev_b32_e64 v245, 8, s31
	v_mov_b32_e32 v247, 1
	v_add_u32_e32 v246, 0x1400, v245
	global_atomic_add v248, v246, v247, s[60:61] sc0

.LBB0_587:
	s_cmp_lt_i32 s59, 4
	s_waitcnt vmcnt(0)
	s_barrier
	s_cbranch_scc1 .LBB0_641
	s_waitcnt vmcnt(0)
	s_barrier
	s_and_saveexec_b64 s[2:3], s[0:1]
	s_cbranch_execz .LBB0_640
	s_waitcnt vmcnt(0) lgkmcnt(0)
	v_mov_b32_e32 v241, 0
	v_lshlrev_b32_e64 v245, 8, s31
	v_mov_b32_e32 v247, 1
	v_add_u32_e32 v246, 0x1400, v245
	global_atomic_add v248, v246, v247, s[60:61] sc0

.Lxb2_go:
	v_add_u32_e32 v249, 1, v244
	ds_write_b32 v241, v249 offset:8
	v_mul_lo_u32 v250, v249, v242
	v_mul_lo_u32 v251, v249, v243
	v_add_u32_e32 v253, 0x2400, v245
	v_mov_b32_e32 v252, 0
	s_waitcnt vmcnt(0)
	buffer_inv sc1
	v_add_u32_e32 v248, 1, v248
	v_cmp_eq_u32_e32 vcc, v248, v250
	s_cbranch_vccz .Lxb2_wait
	s_waitcnt vmcnt(0)
	v_mov_b32_e32 v246, 0x3400
	global_atomic_add v248, v246, v247, s[60:61] sc0
	s_waitcnt vmcnt(0)
	v_add_u32_e32 v248, 1, v248
	v_cmp_ge_u32_e32 vcc, v248, v251
	s_cbranch_vccz .Lxb2_wait
	v_mov_b32_e32 v246, 0x2400
	global_atomic_add v246, v247, s[60:61]
	global_atomic_add v246, v247, s[60:61] offset:256
	global_atomic_add v246, v247, s[60:61] offset:512
	global_atomic_add v246, v247, s[60:61] offset:768
	global_atomic_add v246, v247, s[60:61] offset:1024
	global_atomic_add v246, v247, s[60:61] offset:1280
	global_atomic_add v246, v247, s[60:61] offset:1536
	global_atomic_add v246, v247, s[60:61] offset:1792
	global_atomic_add v246, v247, s[60:61] offset:2048
	global_atomic_add v246, v247, s[60:61] offset:2304
	global_atomic_add v246, v247, s[60:61] offset:2560
	global_atomic_add v246, v247, s[60:61] offset:2816
	global_atomic_add v246, v247, s[60:61] offset:3072
	global_atomic_add v246, v247, s[60:61] offset:3328
	global_atomic_add v246, v247, s[60:61] offset:3584
	global_atomic_add v246, v247, s[60:61] offset:3840
	s_branch .Lxb2_done

.LBB0_657:
	s_cmp_lt_i32 s59, 5
	s_barrier
	s_cbranch_scc1 .LBB0_711
	s_waitcnt vmcnt(0)
	s_barrier
	s_and_saveexec_b64 s[2:3], s[0:1]
	s_cbranch_execz .LBB0_710
	s_waitcnt vmcnt(0) lgkmcnt(0)
	v_mov_b32_e32 v241, 0
	v_lshlrev_b32_e64 v245, 8, s31
	v_mov_b32_e32 v247, 1
	v_add_u32_e32 v246, 0x1400, v245
	global_atomic_add v248, v246, v247, s[60:61] sc0

.LBB0_833:
	s_cmp_lt_i32 s59, 6
	s_waitcnt vmcnt(0)
	s_barrier
	s_cbranch_scc1 .LBB0_887
	s_waitcnt vmcnt(0)
	s_barrier
	s_and_saveexec_b64 s[2:3], s[0:1]
	s_cbranch_execz .LBB0_886
	s_waitcnt vmcnt(0) lgkmcnt(0)
	v_mov_b32_e32 v241, 0
	v_lshlrev_b32_e64 v245, 8, s31
	v_mov_b32_e32 v247, 1
	v_add_u32_e32 v246, 0x1400, v245
	global_atomic_add v248, v246, v247, s[60:61] sc0

.LBB0_986:
	s_cmp_lt_i32 s59, 7
	s_barrier
	s_cbranch_scc1 .LBB0_1040
	s_waitcnt vmcnt(0)
	s_barrier
	s_and_saveexec_b64 s[2:3], s[0:1]
	s_cbranch_execz .LBB0_1039
	s_waitcnt vmcnt(0) lgkmcnt(0)
	v_mov_b32_e32 v241, 0
	v_lshlrev_b32_e64 v245, 8, s31
	v_mov_b32_e32 v247, 1
	v_add_u32_e32 v246, 0x1400, v245
	global_atomic_add v248, v246, v247, s[60:61] sc0

.LBB0_1106:
	s_cmp_lt_i32 s59, 8
	s_barrier
	s_cbranch_scc1 .LBB0_1160
	s_waitcnt vmcnt(0)
	s_barrier
	s_and_saveexec_b64 s[2:3], s[0:1]
	s_cbranch_execz .LBB0_1159
	s_waitcnt vmcnt(0) lgkmcnt(0)
	v_mov_b32_e32 v241, 0
	v_lshlrev_b32_e64 v245, 8, s31
	v_mov_b32_e32 v247, 1
	v_add_u32_e32 v246, 0x1400, v245
	global_atomic_add v248, v246, v247, s[60:61] sc0

.LBB0_1285:
	s_cmp_lt_i32 s59, 10
	s_waitcnt vmcnt(0)
	s_barrier
	s_cbranch_scc1 .LBB0_1339
	s_waitcnt vmcnt(0)
	s_barrier
	s_and_saveexec_b64 s[2:3], s[0:1]
	s_cbranch_execz .LBB0_1338
	s_waitcnt vmcnt(0) lgkmcnt(0)
	v_mov_b32_e32 v241, 0
	v_lshlrev_b32_e64 v245, 8, s31
	v_mov_b32_e32 v247, 1
	v_add_u32_e32 v246, 0x1400, v245
	global_atomic_add v248, v246, v247, s[60:61] sc0

.LBB0_1347:
	s_cmp_lt_i32 s59, 11
	s_barrier
	s_cbranch_scc1 .LBB0_1401
	s_waitcnt vmcnt(0)
	s_barrier
	s_and_saveexec_b64 s[2:3], s[0:1]
	s_cbranch_execz .LBB0_1400
	s_waitcnt vmcnt(0) lgkmcnt(0)
	v_mov_b32_e32 v241, 0
	v_lshlrev_b32_e64 v245, 8, s31
	v_mov_b32_e32 v247, 1
	v_add_u32_e32 v246, 0x1400, v245
	global_atomic_add v248, v246, v247, s[60:61] sc0

.Lcv4_2:
.LBB0_1558:
	s_cmp_lt_i32 s59, 12
	s_waitcnt lgkmcnt(0)
	s_barrier
	s_cbranch_scc1 .LBB0_1612
	s_waitcnt vmcnt(0)
	s_barrier
	s_and_saveexec_b64 s[2:3], s[0:1]
	s_cbranch_execz .LBB0_1611
	s_waitcnt vmcnt(0) lgkmcnt(0)
	v_mov_b32_e32 v241, 0
	v_lshlrev_b32_e64 v245, 8, s31
	v_mov_b32_e32 v247, 1
	v_add_u32_e32 v246, 0x1400, v245
	global_atomic_add v248, v246, v247, s[60:61] sc0

.LBB0_2400:
	s_cmp_lt_i32 s59, 14
	s_waitcnt vmcnt(0)
	s_barrier
	s_cbranch_scc1 .LBB0_2454
	s_waitcnt vmcnt(0)
	s_barrier
	s_and_saveexec_b64 s[2:3], s[0:1]
	s_cbranch_execz .LBB0_2453
	s_waitcnt vmcnt(0) lgkmcnt(0)
	v_mov_b32_e32 v241, 0
	v_lshlrev_b32_e64 v245, 8, s31
	v_mov_b32_e32 v247, 1
	v_add_u32_e32 v246, 0x1400, v245
	global_atomic_add v248, v246, v247, s[60:61] sc0

.LBB0_2462:
	s_cmp_lt_i32 s59, 15
	s_barrier
	s_cbranch_scc1 .LBB0_2516
	s_waitcnt vmcnt(0)
	s_barrier
	s_and_saveexec_b64 s[2:3], s[0:1]
	s_cbranch_execz .LBB0_2515
	s_waitcnt vmcnt(0) lgkmcnt(0)
	v_mov_b32_e32 v241, 0
	v_lshlrev_b32_e64 v245, 8, s31
	v_mov_b32_e32 v247, 1
	v_add_u32_e32 v246, 0x1400, v245
	global_atomic_add v248, v246, v247, s[60:61] sc0

.LBB0_2579:
	s_cmp_lt_i32 s59, 16
	s_waitcnt vmcnt(0)
	s_barrier
	s_cbranch_scc1 .LBB0_2634
	s_waitcnt vmcnt(0)
	s_barrier
	s_and_saveexec_b64 s[2:3], s[0:1]
	s_cbranch_execz .LBB0_2633
	s_waitcnt vmcnt(0) lgkmcnt(0)
	v_mov_b32_e32 v241, 0
	v_lshlrev_b32_e64 v245, 8, s31
	v_mov_b32_e32 v247, 1
	v_add_u32_e32 v246, 0x1400, v245
	global_atomic_add v248, v246, v247, s[60:61] sc0

.LBB0_2702:
	s_cmp_lt_i32 s59, 17
	s_barrier
	s_cbranch_scc1 .LBB0_2756
	s_waitcnt vmcnt(0)
	s_barrier
	s_and_saveexec_b64 s[2:3], s[0:1]
	s_cbranch_execz .LBB0_2755
	s_waitcnt vmcnt(0) lgkmcnt(0)
	v_mov_b32_e32 v241, 0
	v_lshlrev_b32_e64 v245, 8, s31
	v_mov_b32_e32 v247, 1
	v_add_u32_e32 v246, 0x1400, v245
	global_atomic_add v248, v246, v247, s[60:61] sc0

.LBB0_2844:
	s_cmp_lt_i32 s59, 18
	s_barrier
	s_cbranch_scc1 .LBB0_2898
	s_waitcnt vmcnt(0)
	s_barrier
	s_and_saveexec_b64 s[2:3], s[0:1]
	s_cbranch_execz .LBB0_2897
	s_waitcnt vmcnt(0) lgkmcnt(0)
	v_mov_b32_e32 v241, 0
	v_lshlrev_b32_e64 v245, 8, s31
	v_mov_b32_e32 v247, 1
	v_add_u32_e32 v246, 0x1400, v245
	global_atomic_add v248, v246, v247, s[60:61] sc0

.LBB0_3024:
	s_cmp_lt_i32 s59, 20
	s_waitcnt vmcnt(0)
	s_barrier
	s_cbranch_scc1 .LBB0_3078
	s_waitcnt vmcnt(0)
	s_barrier
	s_and_saveexec_b64 s[2:3], s[0:1]
	s_cbranch_execz .LBB0_3077
	s_waitcnt vmcnt(0) lgkmcnt(0)
	v_mov_b32_e32 v241, 0
	v_lshlrev_b32_e64 v245, 8, s31
	v_mov_b32_e32 v247, 1
	v_add_u32_e32 v246, 0x1400, v245
	global_atomic_add v248, v246, v247, s[60:61] sc0

.LBB0_3082:
	s_cmp_lt_u32 s59, 21
	s_barrier
	s_cbranch_scc1 .LBB0_3136
	s_waitcnt vmcnt(0)
	s_barrier
	s_and_saveexec_b64 s[2:3], s[0:1]
	s_cbranch_execz .LBB0_3135
	s_waitcnt vmcnt(0) lgkmcnt(0)
	v_mov_b32_e32 v241, 0
	v_lshlrev_b32_e64 v245, 8, s31
	v_mov_b32_e32 v247, 1
	v_add_u32_e32 v246, 0x1400, v245
	global_atomic_add v248, v246, v247, s[60:61] sc0

.LBB0_3155:
	s_cmp_lt_i32 s59, 22
	s_waitcnt vmcnt(0)
	s_barrier
	s_cbranch_scc1 .LBB0_3209
	s_waitcnt vmcnt(0)
	s_barrier
	s_and_saveexec_b64 s[2:3], s[0:1]
	s_cbranch_execz .LBB0_3208
	s_waitcnt vmcnt(0) lgkmcnt(0)
	v_mov_b32_e32 v241, 0
	v_lshlrev_b32_e64 v245, 8, s31
	v_mov_b32_e32 v247, 1
	v_add_u32_e32 v246, 0x1400, v245
	global_atomic_add v248, v246, v247, s[60:61] sc0

.LBB0_3217:
	s_cmp_lt_i32 s59, 23
	s_barrier
	s_cbranch_scc1 .LBB0_3271
	s_waitcnt vmcnt(0)
	s_barrier
	s_and_saveexec_b64 s[2:3], s[0:1]
	s_cbranch_execz .LBB0_3270
	s_waitcnt vmcnt(0) lgkmcnt(0)
	v_mov_b32_e32 v241, 0
	v_lshlrev_b32_e64 v245, 8, s31
	v_mov_b32_e32 v247, 1
	v_add_u32_e32 v246, 0x1400, v245
	global_atomic_add v248, v246, v247, s[60:61] sc0

.LBB0_3341:
	s_cmp_lt_i32 s59, 24
	s_waitcnt lgkmcnt(0)
	s_barrier
	s_cbranch_scc1 .LBB0_3395
	s_waitcnt vmcnt(0)
	s_barrier
	s_and_saveexec_b64 s[2:3], s[0:1]
	s_cbranch_execz .LBB0_3394
	s_waitcnt vmcnt(0) lgkmcnt(0)
	v_mov_b32_e32 v241, 0
	v_lshlrev_b32_e64 v245, 8, s31
	v_mov_b32_e32 v247, 1
	v_add_u32_e32 v246, 0x1400, v245
	global_atomic_add v248, v246, v247, s[60:61] sc0

.LBB0_3517:
	s_cmp_lt_i32 s59, 26
	s_waitcnt vmcnt(0)
	s_barrier
	s_cbranch_scc1 .LBB0_3571
	s_waitcnt vmcnt(0)
	s_barrier
	s_and_saveexec_b64 s[2:3], s[0:1]
	s_cbranch_execz .LBB0_3570
	s_waitcnt vmcnt(0) lgkmcnt(0)
	v_mov_b32_e32 v241, 0
	v_lshlrev_b32_e64 v245, 8, s31
	v_mov_b32_e32 v247, 1
	v_add_u32_e32 v246, 0x1400, v245
	global_atomic_add v248, v246, v247, s[60:61] sc0
